# v75: mode-0 attention reads-first (first K-fragment ds_reads + 4 exps issued right after the step barrier, before the next tile's DMA address math)
# speedup vs baseline: 1.0070x; 1.0070x over previous
.LBB0_383:
	s_setprio 3
	v_add_u32_e32 v134, s53, v159
	v_exp_f32_e32 v130, v64
	v_exp_f32_e32 v131, v65
	v_exp_f32_e32 v132, v66
	v_exp_f32_e32 v133, v67
	ds_read_b128 v[64:67], v134
	ds_read_b128 v[114:117], v134 offset:512
	s_add_i32 s56, s5, s29
	s_add_i32 s3, s56, -3
	s_ashr_i32 s58, s3, 2
	s_ashr_i32 s59, s58, 31
	s_and_b32 s3, s3, 3
	s_lshl_b64 s[58:59], s[58:59], 21
	s_mul_i32 s78, s3, 0x38000
	s_add_i32 s3, s30, 0
	v_lshl_add_u64 v[80:81], v[152:153], 0, s[58:59]
	s_add_i32 s55, s3, s27
	v_lshl_add_u64 v[80:81], v[80:81], 0, s[78:79]
	s_mov_b32 m0, s55
	s_nop 0
	global_load_lds_dwordx4 v[80:81], off
	v_lshl_add_u64 v[80:81], v[156:157], 0, s[58:59]
	v_lshl_add_u64 v[80:81], v[80:81], 0, s[78:79]
	s_add_i32 m0, s55, 0x2000
	s_mov_b32 s55, s53
	global_load_lds_dwordx4 v[80:81], off
	s_mov_b32 s53, s2
	s_add_i32 s2, s55, 0
	v_exp_f32_e32 v135, v68
	v_add_f32_e32 v68, v3, v7
	v_exp_f32_e32 v136, v69
	s_waitcnt lgkmcnt(0)
	v_mfma_f32_32x32x16_bf16 v[80:95], v[64:67], v[110:113], v[16:31]
	ds_read_b128 v[64:67], v134 offset:2048
	ds_read_b128 v[118:121], v134 offset:2560
	ds_read_b128 v[122:125], v134 offset:4096
	v_exp_f32_e32 v137, v70
	v_exp_f32_e32 v138, v71
	v_exp_f32_e32 v139, v72
	v_exp_f32_e32 v140, v73
	v_exp_f32_e32 v141, v74
	v_exp_f32_e32 v142, v75
	s_waitcnt lgkmcnt(0)
	v_mfma_f32_32x32x16_bf16 v[80:95], v[64:67], v[106:109], v[80:95]
	ds_read_b128 v[126:129], v134 offset:4608
	ds_read_b128 v[64:67], v134 offset:6144
	v_exp_f32_e32 v143, v76
	v_exp_f32_e32 v144, v77
	v_exp_f32_e32 v145, v78
	v_exp_f32_e32 v163, v79
	v_mfma_f32_32x32x16_bf16 v[80:95], v[122:125], v[102:105], v[80:95]
	ds_read_b128 v[122:125], v134 offset:6656
	s_waitcnt lgkmcnt(0)
	v_mfma_f32_32x32x16_bf16 v[80:95], v[64:67], v[98:101], v[80:95]
	v_add_f32_e32 v64, v6, v68
	v_add_f32_e32 v64, v11, v64
	v_add_f32_e32 v64, v10, v64
	v_add_f32_e32 v64, v96, v64
	v_add_f32_e32 v64, v15, v64
	v_add_f32_e32 v64, v97, v64
	v_add_f32_e32 v134, v2, v64
	v_mfma_f32_32x32x16_bf16 v[64:79], v[114:117], v[110:113], v[16:31]
	v_add_f32_e32 v114, v5, v134
	v_add_f32_e32 v114, v4, v114
	v_add_f32_e32 v114, v9, v114
	v_add_f32_e32 v114, v8, v114
	v_add_f32_e32 v114, v12, v114
	v_add_f32_e32 v114, v13, v114
	v_add_f32_e32 v114, v14, v114
	v_mfma_f32_32x32x16_bf16 v[64:79], v[118:121], v[106:109], v[64:79]
	v_add_f32_e32 v114, v130, v114
	v_add_f32_e32 v114, v131, v114
	v_add_f32_e32 v114, v132, v114
	v_add_f32_e32 v114, v133, v114
	v_add_f32_e32 v114, v135, v114
	v_add_f32_e32 v114, v136, v114
	v_add_f32_e32 v114, v137, v114
	v_mfma_f32_32x32x16_bf16 v[64:79], v[126:129], v[102:105], v[64:79]
	v_add_f32_e32 v114, v138, v114
	v_add_f32_e32 v114, v139, v114
	v_add_f32_e32 v114, v140, v114
	v_add_f32_e32 v114, v141, v114
	v_add_f32_e32 v114, v142, v114
	v_add_f32_e32 v114, v143, v114
	v_add_f32_e32 v114, v144, v114
	v_mfma_f32_32x32x16_bf16 v[64:79], v[122:125], v[98:101], v[64:79]
	v_cvt_pk_bf16_f32 v116, v10, v96
	v_cvt_pk_bf16_f32 v10, v2, v5
	v_cvt_pk_bf16_f32 v2, v139, v140
	v_add_f32_e32 v168, v145, v114
	v_cvt_pk_bf16_f32 v114, v3, v7
	v_cvt_pk_bf16_f32 v115, v6, v11
	v_cvt_pk_bf16_f32 v117, v15, v97
	v_cvt_pk_bf16_f32 v11, v4, v9
	v_cvt_pk_bf16_f32 v12, v8, v12
	v_cvt_pk_bf16_f32 v13, v13, v14
	s_setprio 2
	v_cvt_pk_bf16_f32 v6, v130, v131
	v_cvt_pk_bf16_f32 v7, v132, v133
	v_cvt_pk_bf16_f32 v8, v135, v136
	v_cvt_pk_bf16_f32 v9, v137, v138
	v_cvt_pk_bf16_f32 v3, v141, v142
	v_cvt_pk_bf16_f32 v4, v143, v144
	v_cvt_pk_bf16_f32 v5, v145, v163
	v_subrev_u32_e32 v15, 64, v162
	v_cvt_f32_i32_e32 v96, v15
	s_add_i32 s57, s53, 0
	v_add_u32_e32 v14, s57, v0
	ds_read_b64_tr_b16 v[134:135], v14 offset:8192
	ds_read_b64_tr_b16 v[136:137], v14 offset:8704
	ds_read_b64_tr_b16 v[138:139], v14 offset:9216
	ds_read_b64_tr_b16 v[140:141], v14 offset:9728
	ds_read_b64_tr_b16 v[122:123], v14 offset:12288
	ds_read_b64_tr_b16 v[124:125], v14 offset:12800
	ds_read_b64_tr_b16 v[118:119], v14 offset:13312
	ds_read_b64_tr_b16 v[120:121], v14 offset:13824
	ds_read_b64_tr_b16 v[142:143], v14 offset:10240
	ds_read_b64_tr_b16 v[144:145], v14 offset:10752
	ds_read_b64_tr_b16 v[146:147], v14 offset:11264
	ds_read_b64_tr_b16 v[148:149], v14 offset:11776
	v_add_f32_e32 v97, 1.0, v96
	ds_read_b64_tr_b16 v[130:131], v14 offset:14336
	ds_read_b64_tr_b16 v[132:133], v14 offset:14848
	ds_read_b64_tr_b16 v[126:127], v14 offset:15360
	ds_read_b64_tr_b16 v[128:129], v14 offset:15872
	v_and_b32_e32 v14, 0x7fffffff, v96
	v_and_b32_e32 v15, 0x7fffffff, v97
	v_pk_fma_f32 v[14:15], v[154:155], v[14:15], v[80:81]
	v_cmp_le_f32_e64 vcc, |v97|, s77
	v_pk_add_f32 v[164:165], v[96:97], s[26:27] op_sel_hi:[1,0]
	s_waitcnt lgkmcnt(14)
	v_mfma_f32_32x32x16_bf16 v[32:47], v[134:137], v[114:117], v[32:47]
	v_cndmask_b32_e32 v80, v197, v15, vcc
	v_cmp_le_f32_e64 vcc, |v96|, s77
	v_and_b32_e32 v15, 0x7fffffff, v165
	v_add_f32_e64 v134, v96, s18
	v_add_f32_e64 v135, v96, s19
	v_cndmask_b32_e32 v81, v197, v14, vcc
	v_and_b32_e32 v14, 0x7fffffff, v164
	v_pk_fma_f32 v[64:65], v[154:155], v[14:15], v[64:65]
	v_cmp_le_f32_e64 vcc, |v165|, s77
	s_waitcnt lgkmcnt(10)
	v_mfma_f32_32x32x16_bf16 v[48:63], v[122:125], v[114:117], v[48:63]
	v_add_f32_e64 v136, v134, s26
	v_add_f32_e64 v137, v135, s26
	v_cndmask_b32_e32 v14, v197, v65, vcc
	v_cmp_le_f32_e64 vcc, |v164|, s77
	v_add_f32_e64 v164, v96, s8
	v_add_f32_e64 v165, v96, s9
	v_pk_add_f32 v[166:167], v[164:165], s[26:27] op_sel_hi:[1,0]
	v_cndmask_b32_e32 v15, v197, v64, vcc
	v_and_b32_e32 v65, 0x7fffffff, v167
	v_and_b32_e32 v64, 0x7fffffff, v166
	v_pk_fma_f32 v[66:67], v[154:155], v[64:65], v[66:67]
	v_cmp_le_f32_e64 vcc, |v167|, s77
	v_mfma_f32_32x32x16_bf16 v[32:47], v[138:141], v[10:13], v[32:47]
	s_nop 0
	v_cndmask_b32_e32 v64, v197, v67, vcc
	v_cmp_le_f32_e64 vcc, |v166|, s77
	v_and_b32_e32 v67, 0x7fffffff, v165
	s_nop 0
	v_cndmask_b32_e32 v65, v197, v66, vcc
	v_and_b32_e32 v66, 0x7fffffff, v164
	v_pk_fma_f32 v[82:83], v[154:155], v[66:67], v[82:83]
	v_cmp_le_f32_e64 vcc, |v165|, s77
	s_waitcnt lgkmcnt(8)
	v_mfma_f32_32x32x16_bf16 v[48:63], v[118:121], v[10:13], v[48:63]
	v_cndmask_b32_e32 v66, v197, v83, vcc
	v_cmp_le_f32_e64 vcc, |v164|, s77
	v_add_f32_e64 v164, v96, s10
	v_add_f32_e64 v165, v96, s11
	v_add_f32_e64 v166, v164, s26
	v_add_f32_e64 v167, v165, s26
	v_cndmask_b32_e32 v67, v197, v82, vcc
	v_and_b32_e32 v83, 0x7fffffff, v167
	v_and_b32_e32 v82, 0x7fffffff, v166
	v_pk_fma_f32 v[68:69], v[154:155], v[82:83], v[68:69]
	v_cmp_le_f32_e64 vcc, |v167|, s77
	s_waitcnt lgkmcnt(6)
	v_mfma_f32_32x32x16_bf16 v[32:47], v[142:145], v[6:9], v[32:47]
	v_cndmask_b32_e32 v82, v197, v69, vcc
	v_cmp_le_f32_e64 vcc, |v166|, s77
	v_and_b32_e32 v69, 0x7fffffff, v165
	s_nop 0
	v_cndmask_b32_e32 v83, v197, v68, vcc
	v_and_b32_e32 v68, 0x7fffffff, v164
	v_pk_fma_f32 v[84:85], v[154:155], v[68:69], v[84:85]
	v_cmp_le_f32_e64 vcc, |v165|, s77
	s_waitcnt lgkmcnt(2)
	v_mfma_f32_32x32x16_bf16 v[48:63], v[130:133], v[6:9], v[48:63]
	v_cndmask_b32_e32 v68, v197, v85, vcc
	v_cmp_le_f32_e64 vcc, |v164|, s77
	v_add_f32_e64 v164, v96, s12
	v_add_f32_e64 v165, v96, s13
	v_add_f32_e64 v166, v164, s26
	v_add_f32_e64 v167, v165, s26
	s_setprio 1
	v_cndmask_b32_e32 v69, v197, v84, vcc
	v_and_b32_e32 v85, 0x7fffffff, v167
	v_and_b32_e32 v84, 0x7fffffff, v166
	v_pk_fma_f32 v[70:71], v[154:155], v[84:85], v[70:71]
	v_cmp_le_f32_e64 vcc, |v167|, s77
	v_mfma_f32_32x32x16_bf16 v[32:47], v[146:149], v[2:5], v[32:47]
	s_nop 0
	v_cndmask_b32_e32 v84, v197, v71, vcc
	v_cmp_le_f32_e64 vcc, |v166|, s77
	v_and_b32_e32 v71, 0x7fffffff, v165
	s_nop 0
	v_cndmask_b32_e32 v85, v197, v70, vcc
	v_and_b32_e32 v70, 0x7fffffff, v164
	v_pk_fma_f32 v[86:87], v[154:155], v[70:71], v[86:87]
	v_cmp_le_f32_e64 vcc, |v165|, s77
	s_waitcnt lgkmcnt(0)
	v_mfma_f32_32x32x16_bf16 v[48:63], v[126:129], v[2:5], v[48:63]
	v_cndmask_b32_e32 v70, v197, v87, vcc
	v_cmp_le_f32_e64 vcc, |v164|, s77
	v_add_f32_e64 v164, v96, s14
	v_add_f32_e64 v165, v96, s15
	v_add_f32_e64 v166, v164, s26
	v_add_f32_e64 v167, v165, s26
	v_cndmask_b32_e32 v71, v197, v86, vcc
	v_and_b32_e32 v87, 0x7fffffff, v167
	v_and_b32_e32 v86, 0x7fffffff, v166
	v_pk_fma_f32 v[72:73], v[154:155], v[86:87], v[72:73]
	v_cmp_le_f32_e64 vcc, |v167|, s77
	s_nop 1
	v_cndmask_b32_e32 v86, v197, v73, vcc
	v_cmp_le_f32_e64 vcc, |v166|, s77
	v_and_b32_e32 v73, 0x7fffffff, v165
	s_nop 0
	v_cndmask_b32_e32 v87, v197, v72, vcc
	v_and_b32_e32 v72, 0x7fffffff, v164
	v_pk_fma_f32 v[88:89], v[154:155], v[72:73], v[88:89]
	v_cmp_le_f32_e64 vcc, |v165|, s77
	s_nop 1
	v_cndmask_b32_e32 v72, v197, v89, vcc
	v_cmp_le_f32_e64 vcc, |v164|, s77
	v_pk_add_f32 v[164:165], v[96:97], s[16:17] op_sel_hi:[0,1]
	v_pk_add_f32 v[166:167], v[164:165], s[26:27] op_sel_hi:[1,0]
	v_cndmask_b32_e32 v73, v197, v88, vcc
	v_and_b32_e32 v89, 0x7fffffff, v167
	v_and_b32_e32 v88, 0x7fffffff, v166
	v_pk_fma_f32 v[74:75], v[154:155], v[88:89], v[74:75]
	v_cmp_le_f32_e64 vcc, |v167|, s77
	v_pk_add_f32 v[96:97], v[96:97], s[20:21] op_sel_hi:[0,1]
	s_nop 0
	v_cndmask_b32_e32 v88, v197, v75, vcc
	v_cmp_le_f32_e64 vcc, |v166|, s77
	v_and_b32_e32 v75, 0x7fffffff, v165
	s_nop 0
	v_cndmask_b32_e32 v89, v197, v74, vcc
	v_and_b32_e32 v74, 0x7fffffff, v164
	v_pk_fma_f32 v[90:91], v[154:155], v[74:75], v[90:91]
	v_cmp_le_f32_e64 vcc, |v165|, s77
	s_nop 1
	v_cndmask_b32_e32 v74, v197, v91, vcc
	v_cmp_le_f32_e64 vcc, |v164|, s77
	v_and_b32_e32 v91, 0x7fffffff, v137
	s_nop 0
	v_cndmask_b32_e32 v75, v197, v90, vcc
	v_and_b32_e32 v90, 0x7fffffff, v136
	v_pk_fma_f32 v[76:77], v[154:155], v[90:91], v[76:77]
	v_cmp_le_f32_e64 vcc, |v137|, s77
	s_nop 1
	v_cndmask_b32_e32 v90, v197, v77, vcc
	v_cmp_le_f32_e64 vcc, |v136|, s77
	v_and_b32_e32 v77, 0x7fffffff, v135
	s_nop 0
	v_cndmask_b32_e32 v91, v197, v76, vcc
	v_and_b32_e32 v76, 0x7fffffff, v134
	v_pk_fma_f32 v[92:93], v[154:155], v[76:77], v[92:93]
	v_cmp_le_f32_e64 vcc, |v135|, s77
	s_nop 1
	v_cndmask_b32_e32 v76, v197, v93, vcc
	v_cmp_le_f32_e64 vcc, |v134|, s77
	v_pk_add_f32 v[134:135], v[96:97], s[26:27] op_sel_hi:[1,0]
	s_nop 0
	v_cndmask_b32_e32 v77, v197, v92, vcc
	v_and_b32_e32 v93, 0x7fffffff, v135
	v_and_b32_e32 v92, 0x7fffffff, v134
	v_pk_fma_f32 v[78:79], v[154:155], v[92:93], v[78:79]
	v_cmp_le_f32_e64 vcc, |v135|, s77
	s_nop 1
	v_cndmask_b32_e32 v92, v197, v79, vcc
	v_cmp_le_f32_e64 vcc, |v134|, s77
	v_and_b32_e32 v79, 0x7fffffff, v97
	s_nop 0
	v_cndmask_b32_e32 v93, v197, v78, vcc
	v_and_b32_e32 v78, 0x7fffffff, v96
	v_pk_fma_f32 v[94:95], v[154:155], v[78:79], v[94:95]
	v_cmp_le_f32_e64 vcc, |v97|, s77
	s_nop 1
	v_cndmask_b32_e32 v78, v197, v95, vcc
	v_max_f32_e32 v95, v80, v14
	v_cmp_le_f32_e64 vcc, |v96|, s77
	v_max3_f32 v96, v81, v15, v67
	v_max3_f32 v10, v95, v66, v64
	s_setprio 0
	v_max3_f32 v11, v96, v65, v69
	v_max3_f32 v10, v10, v68, v82
	v_max3_f32 v11, v11, v83, v71
	v_max3_f32 v10, v10, v70, v84
	v_max3_f32 v11, v11, v85, v73
	v_max3_f32 v10, v10, v72, v86
	v_max3_f32 v6, v11, v87, v75
	v_max3_f32 v7, v10, v74, v88
	v_cndmask_b32_e32 v79, v197, v94, vcc
	v_max3_f32 v6, v6, v89, v77
	v_max3_f32 v7, v7, v76, v90
	v_max3_f32 v6, v6, v91, v79
	v_max3_f32 v7, v7, v78, v92
	v_add_f32_e32 v94, v163, v168
	v_max3_f32 v2, v6, v93, v7
	v_add_f32_e32 v161, v161, v94
	v_cmp_lt_f32_e32 vcc, s33, v2
	s_cbranch_vccz .LBB0_385
	v_mov_b32_e32 v3, v2
	s_nop 1
	v_permlane32_swap_b32 v2, v3
	s_nop 1
	s_nop 0
	v_max3_f32 v3, v2, v3, 0
	v_exp_f32_e64 v2, -v3
	v_add_f32_e32 v151, v151, v3
	v_xor_b32_e32 v16, 0x80000000, v151
	v_sub_f32_e32 v81, v81, v3
	v_sub_f32_e32 v80, v80, v3
	v_sub_f32_e32 v67, v67, v3
	v_sub_f32_e32 v66, v66, v3
	v_sub_f32_e32 v69, v69, v3
	v_sub_f32_e32 v68, v68, v3
	v_sub_f32_e32 v71, v71, v3
	v_sub_f32_e32 v70, v70, v3
	v_sub_f32_e32 v73, v73, v3
	v_sub_f32_e32 v72, v72, v3
	v_sub_f32_e32 v75, v75, v3
	v_sub_f32_e32 v74, v74, v3
	v_sub_f32_e32 v77, v77, v3
	v_sub_f32_e32 v76, v76, v3
	v_sub_f32_e32 v79, v79, v3
	v_sub_f32_e32 v78, v78, v3
	v_sub_f32_e32 v15, v15, v3
	v_sub_f32_e32 v14, v14, v3
	v_sub_f32_e32 v65, v65, v3
	v_sub_f32_e32 v64, v64, v3
	v_sub_f32_e32 v83, v83, v3
	v_sub_f32_e32 v82, v82, v3
	v_sub_f32_e32 v85, v85, v3
	v_sub_f32_e32 v84, v84, v3
	v_sub_f32_e32 v87, v87, v3
	v_sub_f32_e32 v86, v86, v3
	v_sub_f32_e32 v89, v89, v3
	v_sub_f32_e32 v88, v88, v3
	v_sub_f32_e32 v91, v91, v3
	v_sub_f32_e32 v90, v90, v3
	v_sub_f32_e32 v93, v93, v3
	v_sub_f32_e32 v92, v92, v3
	v_mov_b32_e32 v17, v16
	v_mov_b32_e32 v18, v16
	v_mov_b32_e32 v19, v16
	v_mov_b32_e32 v20, v16
	v_mov_b32_e32 v21, v16
	v_mov_b32_e32 v22, v16
	v_mov_b32_e32 v23, v16
	v_mov_b32_e32 v24, v16
	v_mov_b32_e32 v25, v16
	v_mov_b32_e32 v26, v16
	v_mov_b32_e32 v27, v16
	v_mov_b32_e32 v28, v16
	v_mov_b32_e32 v29, v16
	v_mov_b32_e32 v30, v16
	v_mov_b32_e32 v31, v16
	v_pk_mul_f32 v[46:47], v[46:47], v[2:3] op_sel_hi:[1,0]
	v_pk_mul_f32 v[44:45], v[44:45], v[2:3] op_sel_hi:[1,0]
	v_pk_mul_f32 v[42:43], v[42:43], v[2:3] op_sel_hi:[1,0]
	v_pk_mul_f32 v[40:41], v[40:41], v[2:3] op_sel_hi:[1,0]
	v_pk_mul_f32 v[38:39], v[38:39], v[2:3] op_sel_hi:[1,0]
	v_pk_mul_f32 v[36:37], v[36:37], v[2:3] op_sel_hi:[1,0]
	v_pk_mul_f32 v[34:35], v[34:35], v[2:3] op_sel_hi:[1,0]
	v_pk_mul_f32 v[32:33], v[32:33], v[2:3] op_sel_hi:[1,0]
	v_pk_mul_f32 v[62:63], v[62:63], v[2:3] op_sel_hi:[1,0]
	v_pk_mul_f32 v[60:61], v[60:61], v[2:3] op_sel_hi:[1,0]
	v_pk_mul_f32 v[58:59], v[58:59], v[2:3] op_sel_hi:[1,0]
	v_pk_mul_f32 v[56:57], v[56:57], v[2:3] op_sel_hi:[1,0]
	v_pk_mul_f32 v[54:55], v[54:55], v[2:3] op_sel_hi:[1,0]
	v_pk_mul_f32 v[52:53], v[52:53], v[2:3] op_sel_hi:[1,0]
	v_pk_mul_f32 v[50:51], v[50:51], v[2:3] op_sel_hi:[1,0]
	v_pk_mul_f32 v[48:49], v[48:49], v[2:3] op_sel_hi:[1,0]
	v_mul_f32_e32 v161, v161, v2
